# nt on the proj / up GEMM epilogue stores (C tiles should not displace operand lines in L2)
# baseline (speedup 1.0000x reference)
.LBB0_352:
	v_lshl_or_b32 v148, s66, 8, v152
	v_lshl_add_u32 v157, s65, 8, v1
	v_mov_b64_e32 v[146:147], s[8:9]
	v_ashrrev_i32_e32 v149, 31, v148
	v_mad_i64_i32 v[162:163], s[30:31], v157, s53, v[146:147]
	v_lshlrev_b64 v[148:149], 1, v[148:149]
	v_cvt_pk_bf16_f32 v158, v126, v127
	v_cvt_pk_bf16_f32 v159, v128, v129
	v_cvt_pk_bf16_f32 v160, v122, v123
	v_cvt_pk_bf16_f32 v161, v124, v125
	v_lshl_add_u64 v[162:163], v[162:163], 0, v[148:149]
	global_store_dwordx4 v[162:163], v[158:161], off nt
	s_nop 1
	v_cvt_pk_bf16_f32 v158, v114, v115
	v_cvt_pk_bf16_f32 v159, v116, v117
	v_cvt_pk_bf16_f32 v160, v106, v107
	v_cvt_pk_bf16_f32 v161, v108, v109
	global_store_dwordx4 v[162:163], v[158:161], off offset:256 nt
	v_or_b32_e32 v162, 16, v157
	v_mad_i64_i32 v[162:163], s[30:31], v162, s53, v[146:147]
	v_cvt_pk_bf16_f32 v158, v118, v119
	v_cvt_pk_bf16_f32 v159, v120, v121
	v_cvt_pk_bf16_f32 v160, v110, v111
	v_cvt_pk_bf16_f32 v161, v112, v113
	v_lshl_add_u64 v[162:163], v[162:163], 0, v[148:149]
	global_store_dwordx4 v[162:163], v[158:161], off nt
	s_nop 1
	v_cvt_pk_bf16_f32 v158, v98, v99
	v_cvt_pk_bf16_f32 v159, v100, v101
	v_cvt_pk_bf16_f32 v160, v90, v91
	v_cvt_pk_bf16_f32 v161, v92, v93
	global_store_dwordx4 v[162:163], v[158:161], off offset:256 nt
	v_or_b32_e32 v162, 32, v157
	v_mad_i64_i32 v[162:163], s[30:31], v162, s53, v[146:147]
	v_cvt_pk_bf16_f32 v158, v102, v103
	v_cvt_pk_bf16_f32 v159, v104, v105
	v_cvt_pk_bf16_f32 v160, v94, v95
	v_cvt_pk_bf16_f32 v161, v96, v97
	v_lshl_add_u64 v[162:163], v[162:163], 0, v[148:149]
	global_store_dwordx4 v[162:163], v[158:161], off nt
	s_nop 1
	v_cvt_pk_bf16_f32 v158, v82, v83
	v_cvt_pk_bf16_f32 v159, v84, v85
	v_cvt_pk_bf16_f32 v160, v74, v75
	v_cvt_pk_bf16_f32 v161, v76, v77
	global_store_dwordx4 v[162:163], v[158:161], off offset:256 nt
	v_or_b32_e32 v162, 48, v157
	v_mad_i64_i32 v[162:163], s[30:31], v162, s53, v[146:147]
	v_cvt_pk_bf16_f32 v158, v86, v87
	v_cvt_pk_bf16_f32 v159, v88, v89
	v_cvt_pk_bf16_f32 v160, v78, v79
	v_cvt_pk_bf16_f32 v161, v80, v81
	v_lshl_add_u64 v[162:163], v[162:163], 0, v[148:149]
	global_store_dwordx4 v[162:163], v[158:161], off nt
	s_nop 1
	v_cvt_pk_bf16_f32 v158, v70, v71
	v_cvt_pk_bf16_f32 v159, v72, v73
	v_cvt_pk_bf16_f32 v160, v66, v67
	v_cvt_pk_bf16_f32 v161, v68, v69
	global_store_dwordx4 v[162:163], v[158:161], off offset:256 nt
	v_add_u32_e32 v162, 0x80, v157
	v_mad_i64_i32 v[162:163], s[30:31], v162, s53, v[146:147]
	v_cvt_pk_bf16_f32 v158, v62, v63
	v_cvt_pk_bf16_f32 v159, v64, v65
	v_cvt_pk_bf16_f32 v160, v58, v59
	v_cvt_pk_bf16_f32 v161, v60, v61
	v_lshl_add_u64 v[162:163], v[162:163], 0, v[148:149]
	global_store_dwordx4 v[162:163], v[158:161], off nt
	s_nop 1
	v_cvt_pk_bf16_f32 v158, v50, v51
	v_cvt_pk_bf16_f32 v159, v52, v53
	v_cvt_pk_bf16_f32 v160, v42, v43
	v_cvt_pk_bf16_f32 v161, v44, v45
	global_store_dwordx4 v[162:163], v[158:161], off offset:256 nt
	v_add_u32_e32 v162, 0x90, v157
	v_mad_i64_i32 v[162:163], s[30:31], v162, s53, v[146:147]
	v_cvt_pk_bf16_f32 v158, v54, v55
	v_cvt_pk_bf16_f32 v159, v56, v57
	v_cvt_pk_bf16_f32 v160, v46, v47
	v_cvt_pk_bf16_f32 v161, v48, v49
	v_lshl_add_u64 v[162:163], v[162:163], 0, v[148:149]
	global_store_dwordx4 v[162:163], v[158:161], off nt
	s_nop 1
	v_cvt_pk_bf16_f32 v158, v34, v35
	v_cvt_pk_bf16_f32 v159, v36, v37
	v_cvt_pk_bf16_f32 v160, v26, v27
	v_cvt_pk_bf16_f32 v161, v28, v29
	global_store_dwordx4 v[162:163], v[158:161], off offset:256 nt
	v_add_u32_e32 v162, 0xa0, v157
	v_mad_i64_i32 v[162:163], s[30:31], v162, s53, v[146:147]
	v_add_u32_e32 v157, 0xb0, v157
	v_cvt_pk_bf16_f32 v158, v38, v39
	v_cvt_pk_bf16_f32 v159, v40, v41
	v_cvt_pk_bf16_f32 v160, v30, v31
	v_cvt_pk_bf16_f32 v161, v32, v33
	v_lshl_add_u64 v[162:163], v[162:163], 0, v[148:149]
	v_mad_i64_i32 v[146:147], s[30:31], v157, s53, v[146:147]
	global_store_dwordx4 v[162:163], v[158:161], off nt
	s_nop 1
	v_cvt_pk_bf16_f32 v158, v18, v19
	v_cvt_pk_bf16_f32 v159, v20, v21
	v_cvt_pk_bf16_f32 v160, v10, v11
	v_cvt_pk_bf16_f32 v161, v12, v13
	global_store_dwordx4 v[162:163], v[158:161], off offset:256 nt
	v_lshl_add_u64 v[162:163], v[146:147], 0, v[148:149]
	v_cvt_pk_bf16_f32 v146, v6, v7
	v_cvt_pk_bf16_f32 v147, v8, v9
	v_cvt_pk_bf16_f32 v148, v2, v3
	v_cvt_pk_bf16_f32 v149, v4, v5
	s_nop 0
	v_cvt_pk_bf16_f32 v158, v22, v23
	v_cvt_pk_bf16_f32 v159, v24, v25
	v_cvt_pk_bf16_f32 v160, v14, v15
	v_cvt_pk_bf16_f32 v161, v16, v17
	global_store_dwordx4 v[162:163], v[158:161], off nt
	global_store_dwordx4 v[162:163], v[146:149], off offset:256 nt
	s_cbranch_execnz .LBB0_350
.LBB0_353:
	s_nop 0
	v_lshl_add_u32 v148, s66, 8, v151
	v_lshl_or_b32 v146, s65, 8, v152
	v_ashrrev_i32_e32 v149, 31, v148
	v_ashrrev_i32_e32 v147, 31, v146
	v_lshlrev_b64 v[158:159], 14, v[148:149]
	v_lshl_add_u64 v[158:159], s[10:11], 0, v[158:159]
	v_lshlrev_b64 v[160:161], 1, v[146:147]
	v_lshl_add_u64 v[146:147], v[158:159], 0, v[160:161]
	v_cvt_pk_bf16_f32 v62, v62, v63
	v_cvt_pk_bf16_f32 v63, v64, v65
	v_cvt_pk_bf16_f32 v64, v58, v59
	v_add_co_u32_e32 v58, vcc, s60, v146
	v_cvt_pk_bf16_f32 v114, v114, v115
	v_cvt_pk_bf16_f32 v115, v116, v117
	v_cvt_pk_bf16_f32 v116, v106, v107
	v_or_b32_e32 v106, 16, v148
	s_nop 0
	v_addc_co_u32_e32 v59, vcc, 0, v147, vcc
	v_ashrrev_i32_e32 v107, 31, v106
	v_cvt_pk_bf16_f32 v98, v98, v99
	v_cvt_pk_bf16_f32 v99, v100, v101
	v_cvt_pk_bf16_f32 v100, v90, v91
	v_or_b32_e32 v90, 32, v148
	v_cvt_pk_bf16_f32 v50, v50, v51
	v_cvt_pk_bf16_f32 v51, v52, v53
	v_cvt_pk_bf16_f32 v53, v44, v45
	v_cvt_pk_bf16_f32 v44, v46, v47
	v_add_co_u32_e32 v46, vcc, s61, v146
	v_lshlrev_b64 v[106:107], 14, v[106:107]
	v_ashrrev_i32_e32 v91, 31, v90
	v_cvt_pk_bf16_f32 v82, v82, v83
	v_cvt_pk_bf16_f32 v83, v84, v85
	v_cvt_pk_bf16_f32 v84, v74, v75
	v_or_b32_e32 v74, 48, v148
	v_addc_co_u32_e32 v47, vcc, 0, v147, vcc
	v_lshl_add_u64 v[106:107], s[10:11], 0, v[106:107]
	v_lshlrev_b64 v[90:91], 14, v[90:91]
	v_ashrrev_i32_e32 v75, 31, v74
	v_cvt_pk_bf16_f32 v70, v70, v71
	v_cvt_pk_bf16_f32 v71, v72, v73
	v_cvt_pk_bf16_f32 v72, v66, v67
	v_lshl_add_u64 v[66:67], v[146:147], 0, s[16:17]
	v_cvt_pk_bf16_f32 v34, v34, v35
	v_cvt_pk_bf16_f32 v35, v36, v37
	v_cvt_pk_bf16_f32 v37, v28, v29
	v_cvt_pk_bf16_f32 v28, v30, v31
	v_add_co_u32_e32 v30, vcc, s62, v146
	v_cvt_pk_bf16_f32 v117, v108, v109
	global_store_dwordx4 v[146:147], v[114:117], off offset:256 nt
	v_lshl_add_u64 v[90:91], s[10:11], 0, v[90:91]
	v_lshlrev_b64 v[74:75], 14, v[74:75]
	v_lshl_add_u64 v[114:115], v[106:107], 0, v[160:161]
	v_cvt_pk_bf16_f32 v52, v42, v43
	global_store_dwordx4 v[66:67], v[50:53], off offset:256 nt
	v_addc_co_u32_e32 v31, vcc, 0, v147, vcc
	s_nop 0
	v_lshl_add_u64 v[50:51], v[146:147], 0, s[18:19]
	v_cvt_pk_bf16_f32 v101, v92, v93
	global_store_dwordx4 v[114:115], v[98:101], off offset:256 nt
	v_lshl_add_u64 v[74:75], s[10:11], 0, v[74:75]
	v_cvt_pk_bf16_f32 v36, v26, v27
	global_store_dwordx4 v[50:51], v[34:37], off offset:256 nt
	v_lshl_add_u64 v[98:99], v[90:91], 0, v[160:161]
	v_cvt_pk_bf16_f32 v18, v18, v19
	v_cvt_pk_bf16_f32 v19, v20, v21
	v_cvt_pk_bf16_f32 v21, v12, v13
	v_cvt_pk_bf16_f32 v12, v14, v15
	s_nop 0
	v_lshl_add_u64 v[34:35], v[146:147], 0, s[20:21]
	v_add_co_u32_e32 v14, vcc, s63, v146
	v_cvt_pk_bf16_f32 v85, v76, v77
	global_store_dwordx4 v[98:99], v[82:85], off offset:256 nt
	v_cvt_pk_bf16_f32 v20, v10, v11
	global_store_dwordx4 v[34:35], v[18:21], off offset:256 nt
	v_addc_co_u32_e32 v15, vcc, 0, v147, vcc
	v_lshl_add_u64 v[82:83], v[74:75], 0, v[160:161]
	v_lshl_add_u64 v[18:19], v[146:147], 0, s[22:23]
	v_cvt_pk_bf16_f32 v126, v126, v127
	v_cvt_pk_bf16_f32 v127, v128, v129
	v_cvt_pk_bf16_f32 v128, v122, v123
	v_cvt_pk_bf16_f32 v129, v124, v125
	global_store_dwordx4 v[146:147], v[126:129], off nt
	v_cvt_pk_bf16_f32 v106, v118, v119
	v_cvt_pk_bf16_f32 v107, v120, v121
	v_cvt_pk_bf16_f32 v108, v110, v111
	v_cvt_pk_bf16_f32 v109, v112, v113
	global_store_dwordx4 v[114:115], v[106:109], off nt
	v_cvt_pk_bf16_f32 v90, v102, v103
	v_cvt_pk_bf16_f32 v91, v104, v105
	v_cvt_pk_bf16_f32 v92, v94, v95
	v_cvt_pk_bf16_f32 v93, v96, v97
	global_store_dwordx4 v[98:99], v[90:93], off nt
	v_cvt_pk_bf16_f32 v74, v86, v87
	v_cvt_pk_bf16_f32 v75, v88, v89
	v_cvt_pk_bf16_f32 v76, v78, v79
	v_cvt_pk_bf16_f32 v77, v80, v81
	global_store_dwordx4 v[82:83], v[74:77], off nt
	v_cvt_pk_bf16_f32 v73, v68, v69
	global_store_dwordx4 v[82:83], v[70:73], off offset:256 nt
	v_cvt_pk_bf16_f32 v65, v60, v61
	global_store_dwordx4 v[58:59], v[62:65], off nt
	v_cvt_pk_bf16_f32 v42, v54, v55
	v_cvt_pk_bf16_f32 v43, v56, v57
	v_cvt_pk_bf16_f32 v45, v48, v49
	global_store_dwordx4 v[46:47], v[42:45], off nt
	v_cvt_pk_bf16_f32 v26, v38, v39
	v_cvt_pk_bf16_f32 v27, v40, v41
	v_cvt_pk_bf16_f32 v29, v32, v33
	global_store_dwordx4 v[30:31], v[26:29], off nt
	v_cvt_pk_bf16_f32 v10, v22, v23
	v_cvt_pk_bf16_f32 v11, v24, v25
	v_cvt_pk_bf16_f32 v13, v16, v17
	global_store_dwordx4 v[14:15], v[10:13], off nt
	v_cvt_pk_bf16_f32 v6, v6, v7
	v_cvt_pk_bf16_f32 v7, v8, v9
	v_cvt_pk_bf16_f32 v8, v2, v3
	v_cvt_pk_bf16_f32 v9, v4, v5
	global_store_dwordx4 v[18:19], v[6:9], off offset:256 nt
	s_and_b64 vcc, exec, s[4:5]
	s_mov_b64 s[4:5], -1
	s_cbranch_vccnz .LBB0_332

.LBB0_1176:
	v_lshl_add_u32 v156, s18, 8, v1
	v_lshl_or_b32 v146, s50, 8, v151
	v_cvt_pk_bf16_f32 v126, v126, v127
	v_cvt_pk_bf16_f32 v127, v128, v129
	v_cvt_pk_bf16_f32 v128, v122, v123
	v_mov_b64_e32 v[122:123], s[2:3]
	v_ashrrev_i32_e32 v147, 31, v146
	v_cvt_pk_bf16_f32 v70, v70, v71
	v_cvt_pk_bf16_f32 v71, v72, v73
	v_cvt_pk_bf16_f32 v72, v66, v67
	v_add_u32_e32 v66, 0x80, v156
	v_cvt_pk_bf16_f32 v129, v124, v125
	v_mad_i64_i32 v[148:149], s[20:21], v156, s48, v[122:123]
	v_lshlrev_b64 v[124:125], 1, v[146:147]
	v_cvt_pk_bf16_f32 v62, v62, v63
	v_cvt_pk_bf16_f32 v63, v64, v65
	v_cvt_pk_bf16_f32 v64, v58, v59
	v_mad_i64_i32 v[58:59], s[20:21], v66, s48, v[122:123]
	v_lshl_add_u64 v[146:147], v[148:149], 0, v[124:125]
	v_cvt_pk_bf16_f32 v114, v114, v115
	v_lshl_add_u64 v[58:59], v[58:59], 0, v[124:125]
	v_cvt_pk_bf16_f32 v50, v50, v51
	v_cvt_pk_bf16_f32 v115, v116, v117
	v_cvt_pk_bf16_f32 v116, v106, v107
	v_cvt_pk_bf16_f32 v117, v108, v109
	global_store_dwordx4 v[146:147], v[114:117], off offset:256 nt
	v_cvt_pk_bf16_f32 v51, v52, v53
	v_cvt_pk_bf16_f32 v52, v42, v43
	v_cvt_pk_bf16_f32 v53, v44, v45
	global_store_dwordx4 v[58:59], v[50:53], off offset:256 nt
	v_cvt_pk_bf16_f32 v108, v110, v111
	s_nop 0
	v_or_b32_e32 v114, 16, v156
	v_mad_i64_i32 v[110:111], s[20:21], v114, s48, v[122:123]
	v_add_u32_e32 v50, 0x90, v156
	v_cvt_pk_bf16_f32 v44, v46, v47
	v_mad_i64_i32 v[46:47], s[20:21], v50, s48, v[122:123]
	v_lshl_add_u64 v[110:111], v[110:111], 0, v[124:125]
	v_cvt_pk_bf16_f32 v98, v98, v99
	v_lshl_add_u64 v[46:47], v[46:47], 0, v[124:125]
	v_cvt_pk_bf16_f32 v34, v34, v35
	v_cvt_pk_bf16_f32 v99, v100, v101
	v_cvt_pk_bf16_f32 v100, v90, v91
	v_cvt_pk_bf16_f32 v101, v92, v93
	global_store_dwordx4 v[110:111], v[98:101], off offset:256 nt
	v_cvt_pk_bf16_f32 v35, v36, v37
	v_cvt_pk_bf16_f32 v36, v26, v27
	v_cvt_pk_bf16_f32 v37, v28, v29
	global_store_dwordx4 v[46:47], v[34:37], off offset:256 nt
	v_cvt_pk_bf16_f32 v92, v94, v95
	s_nop 0
	v_or_b32_e32 v98, 32, v156
	v_mad_i64_i32 v[94:95], s[20:21], v98, s48, v[122:123]
	v_add_u32_e32 v34, 0xa0, v156
	v_cvt_pk_bf16_f32 v28, v30, v31
	v_mad_i64_i32 v[30:31], s[20:21], v34, s48, v[122:123]
	v_lshl_add_u64 v[94:95], v[94:95], 0, v[124:125]
	v_cvt_pk_bf16_f32 v82, v82, v83
	v_lshl_add_u64 v[30:31], v[30:31], 0, v[124:125]
	v_cvt_pk_bf16_f32 v18, v18, v19
	v_cvt_pk_bf16_f32 v83, v84, v85
	v_cvt_pk_bf16_f32 v84, v74, v75
	v_cvt_pk_bf16_f32 v85, v76, v77
	global_store_dwordx4 v[94:95], v[82:85], off offset:256 nt
	v_cvt_pk_bf16_f32 v19, v20, v21
	v_cvt_pk_bf16_f32 v20, v10, v11
	v_cvt_pk_bf16_f32 v21, v12, v13
	global_store_dwordx4 v[30:31], v[18:21], off offset:256 nt
	v_cvt_pk_bf16_f32 v76, v78, v79
	s_nop 0
	v_or_b32_e32 v82, 48, v156
	v_mad_i64_i32 v[78:79], s[20:21], v82, s48, v[122:123]
	v_add_u32_e32 v18, 0xb0, v156
	v_cvt_pk_bf16_f32 v12, v14, v15
	v_mad_i64_i32 v[14:15], s[20:21], v18, s48, v[122:123]
	v_lshl_add_u64 v[78:79], v[78:79], 0, v[124:125]
	v_lshl_add_u64 v[14:15], v[14:15], 0, v[124:125]
	s_andn2_b64 vcc, exec, s[4:5]
	s_mov_b64 s[4:5], -1
	global_store_dwordx4 v[146:147], v[126:129], off nt
	v_cvt_pk_bf16_f32 v106, v118, v119
	v_cvt_pk_bf16_f32 v107, v120, v121
	v_cvt_pk_bf16_f32 v109, v112, v113
	global_store_dwordx4 v[110:111], v[106:109], off nt
	v_cvt_pk_bf16_f32 v90, v102, v103
	v_cvt_pk_bf16_f32 v91, v104, v105
	v_cvt_pk_bf16_f32 v93, v96, v97
	global_store_dwordx4 v[94:95], v[90:93], off nt
	v_cvt_pk_bf16_f32 v74, v86, v87
	v_cvt_pk_bf16_f32 v75, v88, v89
	v_cvt_pk_bf16_f32 v77, v80, v81
	global_store_dwordx4 v[78:79], v[74:77], off nt
	v_cvt_pk_bf16_f32 v73, v68, v69
	global_store_dwordx4 v[78:79], v[70:73], off offset:256 nt
	v_cvt_pk_bf16_f32 v65, v60, v61
	global_store_dwordx4 v[58:59], v[62:65], off nt
	v_cvt_pk_bf16_f32 v42, v54, v55
	v_cvt_pk_bf16_f32 v43, v56, v57
	v_cvt_pk_bf16_f32 v45, v48, v49
	global_store_dwordx4 v[46:47], v[42:45], off nt
	v_cvt_pk_bf16_f32 v26, v38, v39
	v_cvt_pk_bf16_f32 v27, v40, v41
	v_cvt_pk_bf16_f32 v29, v32, v33
	global_store_dwordx4 v[30:31], v[26:29], off nt
	v_cvt_pk_bf16_f32 v10, v22, v23
	v_cvt_pk_bf16_f32 v11, v24, v25
	v_cvt_pk_bf16_f32 v13, v16, v17
	global_store_dwordx4 v[14:15], v[10:13], off nt
	v_cvt_pk_bf16_f32 v6, v6, v7
	v_cvt_pk_bf16_f32 v7, v8, v9
	v_cvt_pk_bf16_f32 v8, v2, v3
	v_cvt_pk_bf16_f32 v9, v4, v5
	global_store_dwordx4 v[14:15], v[6:9], off offset:256 nt
	s_cbranch_vccnz .LBB0_1169
	s_andn2_b64 vcc, exec, s[0:1]
	s_cbranch_vccnz .LBB0_1168
	s_barrier
	s_branch .LBB0_1168

.LBB0_1593:
	v_lshl_or_b32 v148, s68, 8, v152
	v_lshl_add_u32 v157, s67, 8, v1
	v_mov_b64_e32 v[146:147], s[8:9]
	v_ashrrev_i32_e32 v149, 31, v148
	v_mad_i64_i32 v[162:163], s[30:31], v157, s55, v[146:147]
	v_lshlrev_b64 v[148:149], 1, v[148:149]
	v_cvt_pk_bf16_f32 v158, v126, v127
	v_cvt_pk_bf16_f32 v159, v128, v129
	v_cvt_pk_bf16_f32 v160, v122, v123
	v_cvt_pk_bf16_f32 v161, v124, v125
	v_lshl_add_u64 v[162:163], v[162:163], 0, v[148:149]
	global_store_dwordx4 v[162:163], v[158:161], off nt
	s_nop 1
	v_cvt_pk_bf16_f32 v158, v114, v115
	v_cvt_pk_bf16_f32 v159, v116, v117
	v_cvt_pk_bf16_f32 v160, v106, v107
	v_cvt_pk_bf16_f32 v161, v108, v109
	global_store_dwordx4 v[162:163], v[158:161], off offset:256 nt
	v_or_b32_e32 v162, 16, v157
	v_mad_i64_i32 v[162:163], s[30:31], v162, s55, v[146:147]
	v_cvt_pk_bf16_f32 v158, v118, v119
	v_cvt_pk_bf16_f32 v159, v120, v121
	v_cvt_pk_bf16_f32 v160, v110, v111
	v_cvt_pk_bf16_f32 v161, v112, v113
	v_lshl_add_u64 v[162:163], v[162:163], 0, v[148:149]
	global_store_dwordx4 v[162:163], v[158:161], off nt
	s_nop 1
	v_cvt_pk_bf16_f32 v158, v98, v99
	v_cvt_pk_bf16_f32 v159, v100, v101
	v_cvt_pk_bf16_f32 v160, v90, v91
	v_cvt_pk_bf16_f32 v161, v92, v93
	global_store_dwordx4 v[162:163], v[158:161], off offset:256 nt
	v_or_b32_e32 v162, 32, v157
	v_mad_i64_i32 v[162:163], s[30:31], v162, s55, v[146:147]
	v_cvt_pk_bf16_f32 v158, v102, v103
	v_cvt_pk_bf16_f32 v159, v104, v105
	v_cvt_pk_bf16_f32 v160, v94, v95
	v_cvt_pk_bf16_f32 v161, v96, v97
	v_lshl_add_u64 v[162:163], v[162:163], 0, v[148:149]
	global_store_dwordx4 v[162:163], v[158:161], off nt
	s_nop 1
	v_cvt_pk_bf16_f32 v158, v82, v83
	v_cvt_pk_bf16_f32 v159, v84, v85
	v_cvt_pk_bf16_f32 v160, v74, v75
	v_cvt_pk_bf16_f32 v161, v76, v77
	global_store_dwordx4 v[162:163], v[158:161], off offset:256 nt
	v_or_b32_e32 v162, 48, v157
	v_mad_i64_i32 v[162:163], s[30:31], v162, s55, v[146:147]
	v_cvt_pk_bf16_f32 v158, v86, v87
	v_cvt_pk_bf16_f32 v159, v88, v89
	v_cvt_pk_bf16_f32 v160, v78, v79
	v_cvt_pk_bf16_f32 v161, v80, v81
	v_lshl_add_u64 v[162:163], v[162:163], 0, v[148:149]
	global_store_dwordx4 v[162:163], v[158:161], off nt
	s_nop 1
	v_cvt_pk_bf16_f32 v158, v70, v71
	v_cvt_pk_bf16_f32 v159, v72, v73
	v_cvt_pk_bf16_f32 v160, v66, v67
	v_cvt_pk_bf16_f32 v161, v68, v69
	global_store_dwordx4 v[162:163], v[158:161], off offset:256 nt
	v_add_u32_e32 v162, 0x80, v157
	v_mad_i64_i32 v[162:163], s[30:31], v162, s55, v[146:147]
	v_cvt_pk_bf16_f32 v158, v62, v63
	v_cvt_pk_bf16_f32 v159, v64, v65
	v_cvt_pk_bf16_f32 v160, v58, v59
	v_cvt_pk_bf16_f32 v161, v60, v61
	v_lshl_add_u64 v[162:163], v[162:163], 0, v[148:149]
	global_store_dwordx4 v[162:163], v[158:161], off nt
	s_nop 1
	v_cvt_pk_bf16_f32 v158, v50, v51
	v_cvt_pk_bf16_f32 v159, v52, v53
	v_cvt_pk_bf16_f32 v160, v42, v43
	v_cvt_pk_bf16_f32 v161, v44, v45
	global_store_dwordx4 v[162:163], v[158:161], off offset:256 nt
	v_add_u32_e32 v162, 0x90, v157
	v_mad_i64_i32 v[162:163], s[30:31], v162, s55, v[146:147]
	v_cvt_pk_bf16_f32 v158, v54, v55
	v_cvt_pk_bf16_f32 v159, v56, v57
	v_cvt_pk_bf16_f32 v160, v46, v47
	v_cvt_pk_bf16_f32 v161, v48, v49
	v_lshl_add_u64 v[162:163], v[162:163], 0, v[148:149]
	global_store_dwordx4 v[162:163], v[158:161], off nt
	s_nop 1
	v_cvt_pk_bf16_f32 v158, v34, v35
	v_cvt_pk_bf16_f32 v159, v36, v37
	v_cvt_pk_bf16_f32 v160, v26, v27
	v_cvt_pk_bf16_f32 v161, v28, v29
	global_store_dwordx4 v[162:163], v[158:161], off offset:256 nt
	v_add_u32_e32 v162, 0xa0, v157
	v_mad_i64_i32 v[162:163], s[30:31], v162, s55, v[146:147]
	v_add_u32_e32 v157, 0xb0, v157
	v_cvt_pk_bf16_f32 v158, v38, v39
	v_cvt_pk_bf16_f32 v159, v40, v41
	v_cvt_pk_bf16_f32 v160, v30, v31
	v_cvt_pk_bf16_f32 v161, v32, v33
	v_lshl_add_u64 v[162:163], v[162:163], 0, v[148:149]
	v_mad_i64_i32 v[146:147], s[30:31], v157, s55, v[146:147]
	global_store_dwordx4 v[162:163], v[158:161], off nt
	s_nop 1
	v_cvt_pk_bf16_f32 v158, v18, v19
	v_cvt_pk_bf16_f32 v159, v20, v21
	v_cvt_pk_bf16_f32 v160, v10, v11
	v_cvt_pk_bf16_f32 v161, v12, v13
	global_store_dwordx4 v[162:163], v[158:161], off offset:256 nt
	v_lshl_add_u64 v[162:163], v[146:147], 0, v[148:149]
	v_cvt_pk_bf16_f32 v146, v6, v7
	v_cvt_pk_bf16_f32 v147, v8, v9
	v_cvt_pk_bf16_f32 v148, v2, v3
	v_cvt_pk_bf16_f32 v149, v4, v5
	s_nop 0
	v_cvt_pk_bf16_f32 v158, v22, v23
	v_cvt_pk_bf16_f32 v159, v24, v25
	v_cvt_pk_bf16_f32 v160, v14, v15
	v_cvt_pk_bf16_f32 v161, v16, v17
	global_store_dwordx4 v[162:163], v[158:161], off nt
	global_store_dwordx4 v[162:163], v[146:149], off offset:256 nt
	s_cbranch_execnz .LBB0_1591
.LBB0_1594:
	s_nop 0
	v_lshl_add_u32 v148, s68, 8, v151
	v_lshl_or_b32 v146, s67, 8, v152
	v_ashrrev_i32_e32 v149, 31, v148
	v_ashrrev_i32_e32 v147, 31, v146
	v_lshlrev_b64 v[158:159], 14, v[148:149]
	v_lshl_add_u64 v[158:159], s[10:11], 0, v[158:159]
	v_lshlrev_b64 v[160:161], 1, v[146:147]
	v_lshl_add_u64 v[146:147], v[158:159], 0, v[160:161]
	v_cvt_pk_bf16_f32 v62, v62, v63
	v_cvt_pk_bf16_f32 v63, v64, v65
	v_cvt_pk_bf16_f32 v64, v58, v59
	v_add_co_u32_e32 v58, vcc, s62, v146
	v_cvt_pk_bf16_f32 v114, v114, v115
	v_cvt_pk_bf16_f32 v115, v116, v117
	v_cvt_pk_bf16_f32 v116, v106, v107
	v_or_b32_e32 v106, 16, v148
	s_nop 0
	v_addc_co_u32_e32 v59, vcc, 0, v147, vcc
	v_ashrrev_i32_e32 v107, 31, v106
	v_cvt_pk_bf16_f32 v98, v98, v99
	v_cvt_pk_bf16_f32 v99, v100, v101
	v_cvt_pk_bf16_f32 v100, v90, v91
	v_or_b32_e32 v90, 32, v148
	v_cvt_pk_bf16_f32 v50, v50, v51
	v_cvt_pk_bf16_f32 v51, v52, v53
	v_cvt_pk_bf16_f32 v53, v44, v45
	v_cvt_pk_bf16_f32 v44, v46, v47
	v_add_co_u32_e32 v46, vcc, s63, v146
	v_lshlrev_b64 v[106:107], 14, v[106:107]
	v_ashrrev_i32_e32 v91, 31, v90
	v_cvt_pk_bf16_f32 v82, v82, v83
	v_cvt_pk_bf16_f32 v83, v84, v85
	v_cvt_pk_bf16_f32 v84, v74, v75
	v_or_b32_e32 v74, 48, v148
	v_addc_co_u32_e32 v47, vcc, 0, v147, vcc
	v_lshl_add_u64 v[106:107], s[10:11], 0, v[106:107]
	v_lshlrev_b64 v[90:91], 14, v[90:91]
	v_ashrrev_i32_e32 v75, 31, v74
	v_cvt_pk_bf16_f32 v70, v70, v71
	v_cvt_pk_bf16_f32 v71, v72, v73
	v_cvt_pk_bf16_f32 v72, v66, v67
	v_lshl_add_u64 v[66:67], v[146:147], 0, s[16:17]
	v_cvt_pk_bf16_f32 v34, v34, v35
	v_cvt_pk_bf16_f32 v35, v36, v37
	v_cvt_pk_bf16_f32 v37, v28, v29
	v_cvt_pk_bf16_f32 v28, v30, v31
	v_add_co_u32_e32 v30, vcc, s64, v146
	v_cvt_pk_bf16_f32 v117, v108, v109
	global_store_dwordx4 v[146:147], v[114:117], off offset:256 nt
	v_lshl_add_u64 v[90:91], s[10:11], 0, v[90:91]
	v_lshlrev_b64 v[74:75], 14, v[74:75]
	v_lshl_add_u64 v[114:115], v[106:107], 0, v[160:161]
	v_cvt_pk_bf16_f32 v52, v42, v43
	global_store_dwordx4 v[66:67], v[50:53], off offset:256 nt
	v_addc_co_u32_e32 v31, vcc, 0, v147, vcc
	s_nop 0
	v_lshl_add_u64 v[50:51], v[146:147], 0, s[18:19]
	v_cvt_pk_bf16_f32 v101, v92, v93
	global_store_dwordx4 v[114:115], v[98:101], off offset:256 nt
	v_lshl_add_u64 v[74:75], s[10:11], 0, v[74:75]
	v_cvt_pk_bf16_f32 v36, v26, v27
	global_store_dwordx4 v[50:51], v[34:37], off offset:256 nt
	v_lshl_add_u64 v[98:99], v[90:91], 0, v[160:161]
	v_cvt_pk_bf16_f32 v18, v18, v19
	v_cvt_pk_bf16_f32 v19, v20, v21
	v_cvt_pk_bf16_f32 v21, v12, v13
	v_cvt_pk_bf16_f32 v12, v14, v15
	s_nop 0
	v_lshl_add_u64 v[34:35], v[146:147], 0, s[20:21]
	v_add_co_u32_e32 v14, vcc, s65, v146
	v_cvt_pk_bf16_f32 v85, v76, v77
	global_store_dwordx4 v[98:99], v[82:85], off offset:256 nt
	v_cvt_pk_bf16_f32 v20, v10, v11
	global_store_dwordx4 v[34:35], v[18:21], off offset:256 nt
	v_addc_co_u32_e32 v15, vcc, 0, v147, vcc
	v_lshl_add_u64 v[82:83], v[74:75], 0, v[160:161]
	v_lshl_add_u64 v[18:19], v[146:147], 0, s[22:23]
	v_cvt_pk_bf16_f32 v126, v126, v127
	v_cvt_pk_bf16_f32 v127, v128, v129
	v_cvt_pk_bf16_f32 v128, v122, v123
	v_cvt_pk_bf16_f32 v129, v124, v125
	global_store_dwordx4 v[146:147], v[126:129], off nt
	v_cvt_pk_bf16_f32 v106, v118, v119
	v_cvt_pk_bf16_f32 v107, v120, v121
	v_cvt_pk_bf16_f32 v108, v110, v111
	v_cvt_pk_bf16_f32 v109, v112, v113
	global_store_dwordx4 v[114:115], v[106:109], off nt
	v_cvt_pk_bf16_f32 v90, v102, v103
	v_cvt_pk_bf16_f32 v91, v104, v105
	v_cvt_pk_bf16_f32 v92, v94, v95
	v_cvt_pk_bf16_f32 v93, v96, v97
	global_store_dwordx4 v[98:99], v[90:93], off nt
	v_cvt_pk_bf16_f32 v74, v86, v87
	v_cvt_pk_bf16_f32 v75, v88, v89
	v_cvt_pk_bf16_f32 v76, v78, v79
	v_cvt_pk_bf16_f32 v77, v80, v81
	global_store_dwordx4 v[82:83], v[74:77], off nt
	v_cvt_pk_bf16_f32 v73, v68, v69
	global_store_dwordx4 v[82:83], v[70:73], off offset:256 nt
	v_cvt_pk_bf16_f32 v65, v60, v61
	global_store_dwordx4 v[58:59], v[62:65], off nt
	v_cvt_pk_bf16_f32 v42, v54, v55
	v_cvt_pk_bf16_f32 v43, v56, v57
	v_cvt_pk_bf16_f32 v45, v48, v49
	global_store_dwordx4 v[46:47], v[42:45], off nt
	v_cvt_pk_bf16_f32 v26, v38, v39
	v_cvt_pk_bf16_f32 v27, v40, v41
	v_cvt_pk_bf16_f32 v29, v32, v33
	global_store_dwordx4 v[30:31], v[26:29], off nt
	v_cvt_pk_bf16_f32 v10, v22, v23
	v_cvt_pk_bf16_f32 v11, v24, v25
	v_cvt_pk_bf16_f32 v13, v16, v17
	global_store_dwordx4 v[14:15], v[10:13], off nt
	v_cvt_pk_bf16_f32 v6, v6, v7
	v_cvt_pk_bf16_f32 v7, v8, v9
	v_cvt_pk_bf16_f32 v8, v2, v3
	v_cvt_pk_bf16_f32 v9, v4, v5
	global_store_dwordx4 v[18:19], v[6:9], off offset:256 nt
	s_and_b64 vcc, exec, s[4:5]
	s_mov_b64 s[4:5], -1
	s_cbranch_vccnz .LBB0_1573
